# residual epilogue second half: waits allow the 15 younger operations (loads and the stores issued since) instead of hipcc's loads-only vmcnt(7..0), no store-ack wait
# speedup vs baseline: 1.0005x; 1.0005x over previous
.LBB0_533:
	v_mul_f32_e32 v171, v171, v171
	v_mul_f32_e32 v167, v167, v167
	v_fmac_f32_e32 v171, v170, v170
	v_mul_f32_e32 v170, v173, v173
	v_fmac_f32_e32 v167, v166, v166
	v_mul_f32_e32 v166, v169, v169
	v_fmac_f32_e32 v170, v172, v172
	v_fmac_f32_e32 v166, v168, v168
	v_add_f32_e32 v170, v171, v170
	v_mul_f32_e32 v171, v175, v175
	v_add_f32_e32 v166, v167, v166
	v_mul_f32_e32 v167, v179, v179
	v_fmac_f32_e32 v171, v174, v174
	v_fmac_f32_e32 v167, v178, v178
	v_add_f32_e32 v170, v171, v170
	v_mul_f32_e32 v171, v177, v177
	v_add_f32_e32 v166, v167, v166
	v_mul_f32_e32 v167, v181, v181
	v_fmac_f32_e32 v171, v176, v176
	v_fmac_f32_e32 v167, v180, v180
	v_add_f32_e32 v170, v171, v170
	v_add_f32_e32 v166, v167, v166
	v_add_f32_e32 v166, v170, v166
	v_mov_b32_e32 v167, v166
	s_nop 1
	v_permlane16_swap_b32_e32 v166, v167
	v_add_f32_e32 v176, v166, v167
	v_mov_b32_e32 v177, v176
	s_waitcnt vmcnt(15)
	v_lshlrev_b32_e32 v166, 16, v162
	v_and_b32_e32 v167, 0xffff0000, v162
	v_lshlrev_b32_e32 v162, 16, v163
	v_and_b32_e32 v163, 0xffff0000, v163
	v_lshlrev_b32_e32 v172, 16, v164
	v_and_b32_e32 v173, 0xffff0000, v164
	v_lshlrev_b32_e32 v168, 16, v165
	v_and_b32_e32 v169, 0xffff0000, v165
	v_mov_b32_e32 v219, v218
	v_permlane32_swap_b32_e32 v176, v177
	v_add_u32_e32 v170, 0x40000, v4
	v_pk_fma_f32 v[164:165], v[218:219], v[68:69], v[162:163]
	v_pk_fma_f32 v[162:163], v[222:223], v[66:67], v[166:167]
	v_pk_fma_f32 v[168:169], v[218:219], v[64:65], v[168:169]
	v_pk_fma_f32 v[166:167], v[222:223], v[62:63], v[172:173]
	s_mov_b64 s[28:29], -1
	s_and_b64 vcc, exec, s[16:17]
	s_cbranch_vccz .LBB0_535
	v_mov_b32_e32 v171, v5
	v_cvt_pk_bf16_f32 v172, v162, v163
	v_cvt_pk_bf16_f32 v173, v164, v165
	v_cvt_pk_bf16_f32 v174, v166, v167
	v_cvt_pk_bf16_f32 v175, v168, v169
	v_lshl_add_u64 v[178:179], v[170:171], 1, s[20:21]
	global_store_dwordx4 v[178:179], v[172:175], off
	s_mov_b64 s[28:29], 0

.LBB0_537:
	s_waitcnt vmcnt(15)
	v_lshlrev_b32_e32 v170, 16, v158
	v_and_b32_e32 v171, 0xffff0000, v158
	v_lshlrev_b32_e32 v158, 16, v159
	v_and_b32_e32 v159, 0xffff0000, v159
	v_lshlrev_b32_e32 v178, 16, v160
	v_and_b32_e32 v179, 0xffff0000, v160
	v_lshlrev_b32_e32 v172, 16, v161
	v_and_b32_e32 v173, 0xffff0000, v161
	v_mov_b32_e32 v219, v218
	v_add_u32_e32 v174, 0x40080, v4
	v_pk_fma_f32 v[160:161], v[218:219], v[60:61], v[158:159]
	v_pk_fma_f32 v[158:159], v[222:223], v[58:59], v[170:171]
	v_pk_fma_f32 v[172:173], v[218:219], v[56:57], v[172:173]
	v_pk_fma_f32 v[170:171], v[222:223], v[54:55], v[178:179]
	s_mov_b64 s[28:29], -1
	s_and_b64 vcc, exec, s[16:17]
	s_cbranch_vccz .LBB0_539
	v_mov_b32_e32 v175, v5
	v_cvt_pk_bf16_f32 v178, v158, v159
	v_cvt_pk_bf16_f32 v179, v160, v161
	v_cvt_pk_bf16_f32 v180, v170, v171
	v_cvt_pk_bf16_f32 v181, v172, v173
	v_lshl_add_u64 v[182:183], v[174:175], 1, s[20:21]
	global_store_dwordx4 v[182:183], v[178:181], off
	s_mov_b64 s[28:29], 0

.LBB0_541:
	v_mul_f32_e32 v163, v163, v163
	v_mul_f32_e32 v159, v159, v159
	v_fmac_f32_e32 v163, v162, v162
	v_mul_f32_e32 v162, v165, v165
	v_fmac_f32_e32 v159, v158, v158
	v_mul_f32_e32 v158, v161, v161
	v_fmac_f32_e32 v162, v164, v164
	v_fmac_f32_e32 v158, v160, v160
	v_add_f32_e32 v162, v163, v162
	v_mul_f32_e32 v163, v167, v167
	v_add_f32_e32 v158, v159, v158
	v_mul_f32_e32 v159, v171, v171
	v_fmac_f32_e32 v163, v166, v166
	v_fmac_f32_e32 v159, v170, v170
	v_add_f32_e32 v162, v163, v162
	v_mul_f32_e32 v163, v169, v169
	v_add_f32_e32 v158, v159, v158
	v_mul_f32_e32 v159, v173, v173
	v_fmac_f32_e32 v163, v168, v168
	v_fmac_f32_e32 v159, v172, v172
	v_add_f32_e32 v162, v163, v162
	v_add_f32_e32 v158, v159, v158
	v_add_f32_e32 v158, v162, v158
	v_mov_b32_e32 v159, v158
	s_nop 1
	v_permlane16_swap_b32_e32 v158, v159
	v_add_f32_e32 v168, v158, v159
	v_mov_b32_e32 v169, v168
	s_waitcnt vmcnt(15)
	v_lshlrev_b32_e32 v158, 16, v154
	v_and_b32_e32 v159, 0xffff0000, v154
	v_lshlrev_b32_e32 v154, 16, v155
	v_and_b32_e32 v155, 0xffff0000, v155
	v_lshlrev_b32_e32 v164, 16, v156
	v_and_b32_e32 v165, 0xffff0000, v156
	v_lshlrev_b32_e32 v160, 16, v157
	v_and_b32_e32 v161, 0xffff0000, v157
	v_mov_b32_e32 v219, v218
	v_permlane32_swap_b32_e32 v168, v169
	v_add_u32_e32 v162, 0x48000, v4
	v_pk_fma_f32 v[156:157], v[218:219], v[52:53], v[154:155]
	v_pk_fma_f32 v[154:155], v[222:223], v[50:51], v[158:159]
	v_pk_fma_f32 v[160:161], v[218:219], v[48:49], v[160:161]
	v_pk_fma_f32 v[158:159], v[222:223], v[46:47], v[164:165]
	s_mov_b64 s[28:29], -1
	s_and_b64 vcc, exec, s[16:17]
	s_cbranch_vccz .LBB0_543
	v_mov_b32_e32 v163, v5
	v_cvt_pk_bf16_f32 v164, v154, v155
	v_cvt_pk_bf16_f32 v165, v156, v157
	v_cvt_pk_bf16_f32 v166, v158, v159
	v_cvt_pk_bf16_f32 v167, v160, v161
	v_lshl_add_u64 v[170:171], v[162:163], 1, s[20:21]
	global_store_dwordx4 v[170:171], v[164:167], off
	s_mov_b64 s[28:29], 0

.LBB0_545:
	s_waitcnt vmcnt(15)
	v_lshlrev_b32_e32 v162, 16, v150
	v_and_b32_e32 v163, 0xffff0000, v150
	v_lshlrev_b32_e32 v150, 16, v151
	v_and_b32_e32 v151, 0xffff0000, v151
	v_lshlrev_b32_e32 v170, 16, v152
	v_and_b32_e32 v171, 0xffff0000, v152
	v_lshlrev_b32_e32 v164, 16, v153
	v_and_b32_e32 v165, 0xffff0000, v153
	v_mov_b32_e32 v219, v218
	v_add_u32_e32 v166, 0x48080, v4
	v_pk_fma_f32 v[152:153], v[218:219], v[44:45], v[150:151]
	v_pk_fma_f32 v[150:151], v[222:223], v[42:43], v[162:163]
	v_pk_fma_f32 v[164:165], v[218:219], v[40:41], v[164:165]
	v_pk_fma_f32 v[162:163], v[222:223], v[38:39], v[170:171]
	s_mov_b64 s[28:29], -1
	s_and_b64 vcc, exec, s[16:17]
	s_cbranch_vccz .LBB0_547
	v_mov_b32_e32 v167, v5
	v_cvt_pk_bf16_f32 v170, v150, v151
	v_cvt_pk_bf16_f32 v171, v152, v153
	v_cvt_pk_bf16_f32 v172, v162, v163
	v_cvt_pk_bf16_f32 v173, v164, v165
	v_lshl_add_u64 v[174:175], v[166:167], 1, s[20:21]
	global_store_dwordx4 v[174:175], v[170:173], off
	s_mov_b64 s[28:29], 0

.LBB0_549:
	v_mul_f32_e32 v155, v155, v155
	v_mul_f32_e32 v151, v151, v151
	v_fmac_f32_e32 v155, v154, v154
	v_mul_f32_e32 v154, v157, v157
	v_fmac_f32_e32 v151, v150, v150
	v_mul_f32_e32 v150, v153, v153
	v_fmac_f32_e32 v154, v156, v156
	v_fmac_f32_e32 v150, v152, v152
	v_add_f32_e32 v154, v155, v154
	v_mul_f32_e32 v155, v159, v159
	v_add_f32_e32 v150, v151, v150
	v_mul_f32_e32 v151, v163, v163
	v_fmac_f32_e32 v155, v158, v158
	v_fmac_f32_e32 v151, v162, v162
	v_add_f32_e32 v154, v155, v154
	v_mul_f32_e32 v155, v161, v161
	v_add_f32_e32 v150, v151, v150
	v_mul_f32_e32 v151, v165, v165
	v_fmac_f32_e32 v155, v160, v160
	v_fmac_f32_e32 v151, v164, v164
	v_add_f32_e32 v154, v155, v154
	v_add_f32_e32 v150, v151, v150
	v_add_f32_e32 v150, v154, v150
	v_mov_b32_e32 v151, v150
	s_nop 1
	v_permlane16_swap_b32_e32 v150, v151
	v_add_f32_e32 v160, v150, v151
	v_mov_b32_e32 v161, v160
	s_waitcnt vmcnt(15)
	v_lshlrev_b32_e32 v150, 16, v146
	v_and_b32_e32 v151, 0xffff0000, v146
	v_lshlrev_b32_e32 v146, 16, v147
	v_and_b32_e32 v147, 0xffff0000, v147
	v_lshlrev_b32_e32 v156, 16, v148
	v_and_b32_e32 v157, 0xffff0000, v148
	v_lshlrev_b32_e32 v152, 16, v149
	v_and_b32_e32 v153, 0xffff0000, v149
	v_mov_b32_e32 v219, v218
	v_permlane32_swap_b32_e32 v160, v161
	v_add_u32_e32 v154, 0x50000, v4
	v_pk_fma_f32 v[148:149], v[218:219], v[36:37], v[146:147]
	v_pk_fma_f32 v[146:147], v[222:223], v[34:35], v[150:151]
	v_pk_fma_f32 v[152:153], v[218:219], v[32:33], v[152:153]
	v_pk_fma_f32 v[150:151], v[222:223], v[30:31], v[156:157]
	s_mov_b64 s[28:29], -1
	s_and_b64 vcc, exec, s[16:17]
	s_cbranch_vccz .LBB0_551
	v_mov_b32_e32 v155, v5
	v_cvt_pk_bf16_f32 v156, v146, v147
	v_cvt_pk_bf16_f32 v157, v148, v149
	v_cvt_pk_bf16_f32 v158, v150, v151
	v_cvt_pk_bf16_f32 v159, v152, v153
	v_lshl_add_u64 v[162:163], v[154:155], 1, s[20:21]
	global_store_dwordx4 v[162:163], v[156:159], off
	s_mov_b64 s[28:29], 0

.LBB0_553:
	s_waitcnt vmcnt(15)
	v_lshlrev_b32_e32 v154, 16, v142
	v_and_b32_e32 v155, 0xffff0000, v142
	v_lshlrev_b32_e32 v142, 16, v143
	v_and_b32_e32 v143, 0xffff0000, v143
	v_lshlrev_b32_e32 v162, 16, v144
	v_and_b32_e32 v163, 0xffff0000, v144
	v_lshlrev_b32_e32 v156, 16, v145
	v_and_b32_e32 v157, 0xffff0000, v145
	v_mov_b32_e32 v219, v218
	v_add_u32_e32 v158, 0x50080, v4
	v_pk_fma_f32 v[144:145], v[218:219], v[28:29], v[142:143]
	v_pk_fma_f32 v[142:143], v[222:223], v[26:27], v[154:155]
	v_pk_fma_f32 v[156:157], v[218:219], v[24:25], v[156:157]
	v_pk_fma_f32 v[154:155], v[222:223], v[22:23], v[162:163]
	s_mov_b64 s[28:29], -1
	s_and_b64 vcc, exec, s[16:17]
	s_cbranch_vccz .LBB0_555
	v_mov_b32_e32 v159, v5
	v_cvt_pk_bf16_f32 v162, v142, v143
	v_cvt_pk_bf16_f32 v163, v144, v145
	v_cvt_pk_bf16_f32 v164, v154, v155
	v_cvt_pk_bf16_f32 v165, v156, v157
	v_lshl_add_u64 v[166:167], v[158:159], 1, s[20:21]
	global_store_dwordx4 v[166:167], v[162:165], off
	s_mov_b64 s[28:29], 0

.LBB0_557:
	v_mul_f32_e32 v147, v147, v147
	v_mul_f32_e32 v143, v143, v143
	v_fmac_f32_e32 v147, v146, v146
	v_mul_f32_e32 v146, v149, v149
	v_fmac_f32_e32 v143, v142, v142
	v_mul_f32_e32 v142, v145, v145
	v_fmac_f32_e32 v146, v148, v148
	v_fmac_f32_e32 v142, v144, v144
	v_add_f32_e32 v146, v147, v146
	v_mul_f32_e32 v147, v151, v151
	v_add_f32_e32 v142, v143, v142
	v_mul_f32_e32 v143, v155, v155
	v_fmac_f32_e32 v147, v150, v150
	v_fmac_f32_e32 v143, v154, v154
	v_add_f32_e32 v146, v147, v146
	v_mul_f32_e32 v147, v153, v153
	v_add_f32_e32 v142, v143, v142
	v_mul_f32_e32 v143, v157, v157
	v_fmac_f32_e32 v147, v152, v152
	v_fmac_f32_e32 v143, v156, v156
	v_add_f32_e32 v146, v147, v146
	v_add_f32_e32 v142, v143, v142
	v_add_f32_e32 v142, v146, v142
	v_mov_b32_e32 v143, v142
	s_nop 1
	v_permlane16_swap_b32_e32 v142, v143
	v_add_f32_e32 v152, v142, v143
	v_mov_b32_e32 v153, v152
	s_waitcnt vmcnt(15)
	v_lshlrev_b32_e32 v142, 16, v138
	v_and_b32_e32 v143, 0xffff0000, v138
	v_lshlrev_b32_e32 v138, 16, v139
	v_and_b32_e32 v139, 0xffff0000, v139
	v_lshlrev_b32_e32 v148, 16, v140
	v_and_b32_e32 v149, 0xffff0000, v140
	v_lshlrev_b32_e32 v144, 16, v141
	v_and_b32_e32 v145, 0xffff0000, v141
	v_mov_b32_e32 v219, v218
	v_permlane32_swap_b32_e32 v152, v153
	v_add_u32_e32 v146, 0x58000, v4
	v_pk_fma_f32 v[140:141], v[218:219], v[20:21], v[138:139]
	v_pk_fma_f32 v[138:139], v[222:223], v[18:19], v[142:143]
	v_pk_fma_f32 v[144:145], v[218:219], v[16:17], v[144:145]
	v_pk_fma_f32 v[142:143], v[222:223], v[14:15], v[148:149]
	s_mov_b64 s[28:29], -1
	s_and_b64 vcc, exec, s[16:17]
	s_cbranch_vccz .LBB0_559
	v_mov_b32_e32 v147, v5
	v_cvt_pk_bf16_f32 v148, v138, v139
	v_cvt_pk_bf16_f32 v149, v140, v141
	v_cvt_pk_bf16_f32 v150, v142, v143
	v_cvt_pk_bf16_f32 v151, v144, v145
	v_lshl_add_u64 v[154:155], v[146:147], 1, s[20:21]
	global_store_dwordx4 v[154:155], v[148:151], off
	s_mov_b64 s[28:29], 0

.LBB0_561:
	s_waitcnt vmcnt(15)
	v_lshlrev_b32_e32 v146, 16, v134
	v_and_b32_e32 v147, 0xffff0000, v134
	v_lshlrev_b32_e32 v134, 16, v135
	v_and_b32_e32 v135, 0xffff0000, v135
	v_lshlrev_b32_e32 v154, 16, v136
	v_and_b32_e32 v155, 0xffff0000, v136
	v_lshlrev_b32_e32 v148, 16, v137
	v_and_b32_e32 v149, 0xffff0000, v137
	v_mov_b32_e32 v219, v218
	v_add_u32_e32 v150, 0x58080, v4
	v_pk_fma_f32 v[136:137], v[218:219], v[12:13], v[134:135]
	v_pk_fma_f32 v[134:135], v[222:223], v[10:11], v[146:147]
	v_pk_fma_f32 v[148:149], v[218:219], v[8:9], v[148:149]
	v_pk_fma_f32 v[146:147], v[222:223], v[6:7], v[154:155]
	s_mov_b64 s[28:29], -1
	s_and_b64 vcc, exec, s[16:17]
	s_cbranch_vccz .LBB0_563
	v_mov_b32_e32 v151, v5
	v_cvt_pk_bf16_f32 v154, v134, v135
	v_cvt_pk_bf16_f32 v155, v136, v137
	v_cvt_pk_bf16_f32 v156, v146, v147
	v_cvt_pk_bf16_f32 v157, v148, v149
	v_lshl_add_u64 v[158:159], v[150:151], 1, s[20:21]
	global_store_dwordx4 v[158:159], v[154:157], off
	s_mov_b64 s[28:29], 0
